# pool phase tile remap: each XCD takes 64 consecutive 32-token tiles so the 15-row window overlap is re-read from its own L2
# speedup vs baseline: 1.0007x; 1.0007x over previous
.LBB0_1214:
	s_and_b64 vcc, exec, s[0:1]
	s_cbranch_vccz .LBB0_1236
	v_readfirstlane_b32 s0, v204
	s_lshr_b32 s0, s0, 8
	v_readlane_b32 s1, v250, 43
	s_add_i32 s12, s0, s1
	s_and_b32 s0, s12, 1
	s_bfe_u32 s1, s12, 0x50004
	s_lshl_b32 s1, s1, 1
	s_or_b32 s0, s0, s1
	s_bfe_u32 s1, s12, 0x30001
	s_lshl_b32 s1, s1, 6
	s_or_b32 s12, s0, s1
	v_mov_b32_e32 v2, v205
	s_cmpk_gt_i32 s12, 0x1ff
	v_readlane_b32 s20, v250, 35
	s_cbranch_scc1 .LBB0_1276
	v_ashrrev_i32_e32 v12, 6, v2
	v_and_b32_e32 v3, 63, v2
	v_readlane_b32 s16, v250, 9
	v_lshlrev_b32_e32 v0, 4, v3
	v_readlane_b32 s17, v250, 10
	v_lshlrev_b32_e32 v2, 2, v2
	v_lshlrev_b32_e64 v13, v12, 2
	v_readlane_b32 s2, v250, 48
	v_lshl_add_u64 v[6:7], s[16:17], 0, v[0:1]
	v_cmp_eq_u32_e64 s[6:7], 0, v3
	v_ashrrev_i32_e32 v3, 31, v2
	v_readlane_b32 s3, v250, 49
	s_lshl_b32 s13, s12, 5
	v_lshlrev_b32_e32 v0, 2, v13
	v_readlane_b32 s0, v252, 55
	v_cmp_gt_i32_e64 s[4:5], 47, v12
	v_sub_u32_e32 v14, 1, v13
	v_cmp_lt_i32_e64 s[8:9], 1, v13
	v_lshl_add_u64 v[8:9], v[2:3], 2, s[16:17]
	v_lshl_add_u64 v[10:11], v[2:3], 1, s[2:3]
	v_lshl_add_u32 v15, v12, 2, s80
	v_sub_u32_e32 v16, 0, v0
	v_sub_u32_e32 v17, s0, v0
	v_sub_u32_e32 v18, s13, v13
	v_sub_u32_e32 v19, 0, v13
	v_readlane_b32 s18, v250, 11
	v_readlane_b32 s19, v250, 12
	s_branch .LBB0_1218
